# attention loop softmax stabilised by the Cauchy-Schwarz score bound (no per-step row max / exchange / rescale); XCD queues can steal from other classes
# speedup vs baseline: 1.0531x; 1.0071x over previous
.LBB0_1306:
	s_mov_b32 s98, 0
	s_and_b32 s62, s80, 7
	s_lshl_b32 s62, s62, 6
	s_add_u32 s8, s86, 0x1e28f900
	s_addc_u32 s9, s87, 0
	s_add_u32 s8, s8, s62
	s_addc_u32 s9, s9, 0
	s_and_saveexec_b64 s[0:1], s[82:83]
	s_cbranch_execz .LBB0_1310
	s_mov_b64 s[6:7], exec
	v_mbcnt_lo_u32_b32 v2, s6, 0
	v_mbcnt_hi_u32_b32 v2, s7, v2
	v_cmp_eq_u32_e32 vcc, 0, v2
	s_and_saveexec_b64 s[4:5], vcc
	s_cbranch_execz .LBB0_1309
	s_bcnt1_i32_b64 s3, s[6:7]
	v_mov_b32_e32 v3, 0
	v_mov_b32_e32 v4, s3
	global_atomic_add v3, v3, v4, s[8:9] sc0

.Lqa_top:
	s_add_i32 s62, s80, s98
	s_and_b32 s62, s62, 7
	s_cmp_lt_u32 s26, 4
	s_cbranch_scc0 .Lqa_prompt
	s_lshl_b32 s26, s26, 3
	s_add_i32 s26, s26, s62
	s_branch .Lqa_done
.Lqa_prompt:
	s_add_i32 s63, s26, -4
	s_and_b32 s64, s62, 1
	s_lshr_b32 s65, s62, 1
	s_mov_b32 s67, 0
	s_movk_i32 s66, 45
	s_sub_i32 s59, 64, s66
	s_cmp_eq_u32 s64, 0
	s_cselect_b32 s59, s59, s66
	s_cmp_lt_u32 s63, s59
	s_cbranch_scc1 .Lqa_found
	s_sub_i32 s63, s63, s59
	s_addk_i32 s67, 0x100
	s_movk_i32 s66, 37
	s_sub_i32 s59, 64, s66
	s_cmp_eq_u32 s64, 0
	s_cselect_b32 s59, s59, s66
	s_cmp_lt_u32 s63, s59
	s_cbranch_scc1 .Lqa_found
	s_sub_i32 s63, s63, s59
	s_addk_i32 s67, 0x100
	s_movk_i32 s66, 33
	s_sub_i32 s59, 64, s66
	s_cmp_eq_u32 s64, 0
	s_cselect_b32 s59, s59, s66
	s_cmp_lt_u32 s63, s59
	s_cbranch_scc1 .Lqa_found
	s_sub_i32 s63, s63, s59
	s_addk_i32 s67, 0x100
	s_movk_i32 s66, 32
	s_sub_i32 s59, 64, s66
	s_cmp_eq_u32 s64, 0
	s_cselect_b32 s59, s59, s66
	s_cmp_lt_u32 s63, s59
	s_cbranch_scc1 .Lqa_found
	s_sub_i32 s63, s63, s59
	s_addk_i32 s67, 0x100
	s_cmp_lt_u32 s63, 0x41
	s_cbranch_scc1 .Lqa_lru
	s_sub_i32 s63, s63, 0x41
	s_add_i32 s98, s98, 1
	s_cmp_ge_u32 s98, 8
	s_cbranch_scc1 .LBB0_1418
	s_add_i32 s62, s80, s98
	s_and_b32 s62, s62, 7
	s_lshl_b32 s63, s62, 6
	s_add_u32 s8, s86, 0x1e28f900
	s_addc_u32 s9, s87, 0
	s_add_u32 s8, s8, s63
	s_addc_u32 s9, s9, 0
	s_barrier
	s_and_saveexec_b64 s[0:1], s[82:83]
	s_cbranch_execz .Lqa_nodraw
	v_mov_b32_e32 v2, 0
	v_mov_b32_e32 v3, 1
	s_nop 1
	global_atomic_add v3, v2, v3, s[8:9] sc0
	s_waitcnt vmcnt(0)
	v_mov_b32_e32 v2, s3
	ds_write_b32 v2, v3
.Lqa_nodraw:
	s_or_b64 exec, exec, s[0:1]
	s_waitcnt lgkmcnt(0)
	s_barrier
	v_mov_b32_e32 v2, s3
	ds_read_b32 v2, v2
	s_waitcnt lgkmcnt(0)
	v_readfirstlane_b32 s26, v2
	s_nop 3
	s_branch .Lqa_top
.Lqa_lru:
	s_lshl_b32 s63, s63, 3
	s_add_i32 s26, s63, s62
	s_addk_i32 s26, 0x420
	s_branch .Lqa_done

.LBB0_1377:
	s_and_b64 vcc, exec, s[0:1]
	s_waitcnt lgkmcnt(0)
	s_barrier
	s_cbranch_vccnz .LBB0_1402
	v_max_f32_e32 v66, v153, v153
	v_max_f32_e32 v67, v152, v152
	v_max_f32_e32 v66, v67, v66
	v_max3_f32 v66, v150, v151, v66
	v_mul_f32_e32 v67, 0x4f800000, v66
	v_cmp_gt_f32_e32 vcc, s38, v66
	v_max_f32_e32 v70, v148, v148
	s_add_i32 s6, s26, -6
	v_cndmask_b32_e32 v66, v66, v67, vcc
	v_sqrt_f32_e32 v67, v66
	s_mov_b32 s35, 5
	v_add_u32_e32 v68, -1, v67
	v_fma_f32 v69, -v68, v67, v66
	v_cmp_ge_f32_e64 s[0:1], 0, v69
	v_add_u32_e32 v69, 1, v67
	s_nop 0
	v_cndmask_b32_e64 v68, v67, v68, s[0:1]
	v_fma_f32 v67, -v69, v67, v66
	v_cmp_lt_f32_e64 s[0:1], 0, v67
	s_nop 1
	v_cndmask_b32_e64 v67, v68, v69, s[0:1]
	v_max_f32_e32 v69, v149, v149
	v_max_f32_e32 v69, v70, v69
	v_max3_f32 v69, v146, v147, v69
	v_mul_f32_e32 v70, 0x4f800000, v69
	v_cmp_gt_f32_e64 s[0:1], s38, v69
	v_mul_f32_e32 v68, 0x37800000, v67
	v_cndmask_b32_e32 v67, v67, v68, vcc
	v_cndmask_b32_e64 v70, v69, v70, s[0:1]
	v_sqrt_f32_e32 v69, v70
	v_cmp_class_f32_e32 vcc, v66, v213
	s_nop 1
	v_cndmask_b32_e32 v178, v67, v66, vcc
	v_add_u32_e32 v66, -1, v69
	v_fma_f32 v67, -v66, v69, v70
	v_cmp_ge_f32_e32 vcc, 0, v67
	v_add_u32_e32 v67, 1, v69
	v_fma_f32 v68, -v67, v69, v70
	v_cndmask_b32_e32 v66, v69, v66, vcc
	v_cmp_lt_f32_e32 vcc, 0, v68
	s_nop 1
	v_cndmask_b32_e32 v66, v66, v67, vcc
	v_mul_f32_e32 v67, 0x37800000, v66
	v_cndmask_b32_e64 v71, v66, v67, s[0:1]
	v_mov_b32_e32 v66, s39
	ds_read_b128 v[66:69], v66
	v_cmp_class_f32_e32 vcc, v70, v213
	s_add_i32 s0, 0, 0x11c20
	s_nop 0
	v_cndmask_b32_e32 v179, v71, v70, vcc
	v_mov_b32_e32 v70, s0
	ds_read_b128 v[70:73], v70
	s_waitcnt lgkmcnt(1)
	v_max_f32_e32 v69, v69, v69
	v_max_f32_e32 v68, v68, v68
	v_min_f32_e32 v68, v68, v69
	v_min3_f32 v67, v66, v67, v68
	s_waitcnt lgkmcnt(0)
	v_max_f32_e32 v66, v73, v73
	v_max_f32_e32 v68, v72, v72
	v_min_f32_e32 v66, v68, v66
	v_min3_f32 v66, v70, v71, v66
	s_mov_b32 s0, 0xc2200000
	v_pk_add_f32 v[180:181], v[66:67], s[0:1] op_sel_hi:[1,0]
	s_lshl_b32 s0, s26, 2
	s_add_i32 s0, s0, 0
	s_add_i32 s13, s0, 0x117e8
	s_lshl_b32 s0, s26, 6
	s_sub_i32 s12, 0, s0
	s_lshl_b32 s0, s26, 1
	s_sub_i32 s0, s71, s0
	v_mov_b32_e32 v200, v179
	s_add_i32 s34, s0, 8
	v_mov_b32_e32 v248, s13
	ds_read2_b32 v[248:249], v248 offset0:5 offset1:133
	s_cmp_eq_u32 s70, 0
	s_cselect_b64 vcc, -1, 0
	s_waitcnt lgkmcnt(0)
	v_mul_f32_e32 v248, v178, v248
	v_mul_f32_e32 v249, v179, v249
	v_cndmask_b32_e32 v248, v249, v248, vcc
	v_sub_f32_e32 v250, v226, v248
	v_exp_f32_e32 v250, v250
	v_mov_b32_e32 v226, v248
	s_nop 0
	v_mul_f32_e32 v224, v224, v250
	v_pk_mul_f32 v[2:3], v[2:3], v[250:251] op_sel_hi:[1,0]
	v_pk_mul_f32 v[4:5], v[4:5], v[250:251] op_sel_hi:[1,0]
	v_pk_mul_f32 v[6:7], v[6:7], v[250:251] op_sel_hi:[1,0]
	v_pk_mul_f32 v[8:9], v[8:9], v[250:251] op_sel_hi:[1,0]
	v_pk_mul_f32 v[10:11], v[10:11], v[250:251] op_sel_hi:[1,0]
	v_pk_mul_f32 v[12:13], v[12:13], v[250:251] op_sel_hi:[1,0]
	v_pk_mul_f32 v[14:15], v[14:15], v[250:251] op_sel_hi:[1,0]
	v_pk_mul_f32 v[16:17], v[16:17], v[250:251] op_sel_hi:[1,0]
	v_pk_mul_f32 v[18:19], v[18:19], v[250:251] op_sel_hi:[1,0]
	v_pk_mul_f32 v[20:21], v[20:21], v[250:251] op_sel_hi:[1,0]
	v_pk_mul_f32 v[22:23], v[22:23], v[250:251] op_sel_hi:[1,0]
	v_pk_mul_f32 v[24:25], v[24:25], v[250:251] op_sel_hi:[1,0]
	v_pk_mul_f32 v[26:27], v[26:27], v[250:251] op_sel_hi:[1,0]
	v_pk_mul_f32 v[28:29], v[28:29], v[250:251] op_sel_hi:[1,0]
	v_pk_mul_f32 v[30:31], v[30:31], v[250:251] op_sel_hi:[1,0]
	v_pk_mul_f32 v[32:33], v[32:33], v[250:251] op_sel_hi:[1,0]
	v_pk_mul_f32 v[34:35], v[34:35], v[250:251] op_sel_hi:[1,0]
	v_pk_mul_f32 v[36:37], v[36:37], v[250:251] op_sel_hi:[1,0]
	v_pk_mul_f32 v[38:39], v[38:39], v[250:251] op_sel_hi:[1,0]
	v_pk_mul_f32 v[40:41], v[40:41], v[250:251] op_sel_hi:[1,0]
	v_pk_mul_f32 v[42:43], v[42:43], v[250:251] op_sel_hi:[1,0]
	v_pk_mul_f32 v[44:45], v[44:45], v[250:251] op_sel_hi:[1,0]
	v_pk_mul_f32 v[46:47], v[46:47], v[250:251] op_sel_hi:[1,0]
	v_pk_mul_f32 v[48:49], v[48:49], v[250:251] op_sel_hi:[1,0]
	v_pk_mul_f32 v[50:51], v[50:51], v[250:251] op_sel_hi:[1,0]
	v_pk_mul_f32 v[52:53], v[52:53], v[250:251] op_sel_hi:[1,0]
	v_pk_mul_f32 v[54:55], v[54:55], v[250:251] op_sel_hi:[1,0]
	v_pk_mul_f32 v[56:57], v[56:57], v[250:251] op_sel_hi:[1,0]
	v_pk_mul_f32 v[58:59], v[58:59], v[250:251] op_sel_hi:[1,0]
	v_pk_mul_f32 v[60:61], v[60:61], v[250:251] op_sel_hi:[1,0]
	v_pk_mul_f32 v[62:63], v[62:63], v[250:251] op_sel_hi:[1,0]
	v_pk_mul_f32 v[64:65], v[64:65], v[250:251] op_sel_hi:[1,0]
	s_branch .LBB0_1380

.LBB0_1384:
	s_add_i32 s0, s34, -2
	s_cmp_lt_i32 s0, 1
	s_cbranch_scc1 .LBB0_1388
	s_waitcnt lgkmcnt(7)
	v_mfma_f32_32x32x16_bf16 v[82:97], v[66:69], v[130:133], 0
	s_waitcnt lgkmcnt(5)
	v_mfma_f32_32x32x16_bf16 v[66:81], v[70:73], v[130:133], 0
	v_mfma_f32_32x32x16_bf16 v[82:97], v[146:149], v[134:137], v[82:97]
	s_waitcnt lgkmcnt(4)
	v_mfma_f32_32x32x16_bf16 v[66:81], v[150:153], v[134:137], v[66:81]
	s_waitcnt lgkmcnt(3)
	v_mfma_f32_32x32x16_bf16 v[82:97], v[154:157], v[138:141], v[82:97]
	s_waitcnt lgkmcnt(1)
	v_mfma_f32_32x32x16_bf16 v[66:81], v[162:165], v[138:141], v[66:81]
	v_mfma_f32_32x32x16_bf16 v[82:97], v[158:161], v[142:145], v[82:97]
	ds_read_b128 v[162:165], v221 offset:17408
	ds_read_b128 v[146:149], v221 offset:17440
	ds_read_b128 v[166:169], v221 offset:22016
	ds_read_b128 v[150:153], v221 offset:22048
	ds_read_b128 v[170:173], v221 offset:26624
	ds_read_b128 v[154:157], v221 offset:26656
	ds_read_b128 v[174:177], v221 offset:31232
	ds_read_b128 v[158:161], v221 offset:31264
	s_waitcnt lgkmcnt(8)
	v_mfma_f32_32x32x16_bf16 v[66:81], v[228:231], v[142:145], v[66:81]
	v_add_u32_e32 v184, s12, v223
	v_add_u32_e32 v184, 0xc0, v184
	v_cvt_f32_i32_e32 v236, v184
	v_mul_f32_e64 v245, -v201, v236
	v_mov_b32_e32 v188, v82
	v_fmamk_f32 v234, v201, 0x3f800000, v83
	v_fmamk_f32 v229, v201, 0x40000000, v84
	v_fmamk_f32 v231, v201, 0x40400000, v85
	v_fmamk_f32 v184, v201, 0x41000000, v86
	v_fmamk_f32 v227, v201, 0x41100000, v87
	v_fmamk_f32 v86, v201, 0x41200000, v88
	v_fmamk_f32 v88, v201, 0x41300000, v89
	v_fmamk_f32 v233, v201, 0x42000000, v66
	v_fmamk_f32 v235, v201, 0x42040000, v67
	v_fmamk_f32 v230, v201, 0x42080000, v68
	v_fmamk_f32 v232, v201, 0x420c0000, v69
	v_fmamk_f32 v185, v201, 0x42200000, v70
	v_fmamk_f32 v228, v201, 0x42240000, v71
	v_fmamk_f32 v87, v201, 0x42280000, v72
	v_fmamk_f32 v89, v201, 0x422c0000, v73
	v_fmamk_f32 v82, v201, 0x41800000, v90
	v_fmamk_f32 v84, v201, 0x41880000, v91
	v_fmamk_f32 v83, v201, 0x42400000, v74
	v_fmamk_f32 v85, v201, 0x42440000, v75
	v_fmamk_f32 v74, v201, 0x41900000, v92
	v_fmamk_f32 v75, v201, 0x42480000, v76
	v_fmamk_f32 v76, v201, 0x41980000, v93
	v_fmamk_f32 v77, v201, 0x424c0000, v77
	v_fmamk_f32 v70, v201, 0x41c00000, v94
	v_fmamk_f32 v72, v201, 0x41c80000, v95
	v_fmamk_f32 v71, v201, 0x42600000, v78
	v_fmamk_f32 v73, v201, 0x42640000, v79
	v_fmamk_f32 v67, v201, 0x42680000, v80
	v_fmamk_f32 v69, v201, 0x426c0000, v81
	v_fmamk_f32 v66, v201, 0x41d00000, v96
	v_fmamk_f32 v68, v201, 0x41d80000, v97
.LBB0_1387:
	v_sub_f32_e32 v246, v226, v245
	v_sub_f32_e32 v78, v188, v246
	v_exp_f32_e32 v236, v78
	v_sub_f32_e32 v78, v233, v246
	v_exp_f32_e32 v237, v78
	v_sub_f32_e32 v78, v234, v246
	v_sub_f32_e32 v79, v235, v246
	v_exp_f32_e32 v78, v78
	v_exp_f32_e32 v188, v79
	v_add_f32_e32 v79, v236, v237
	v_sub_f32_e32 v86, v86, v246
	v_sub_f32_e32 v82, v82, v246
	v_pk_add_f32 v[80:81], v[78:79], v[188:189]
	v_sub_f32_e32 v79, v229, v246
	v_pk_add_f32 v[80:81], v[80:81], v[80:81] op_sel_hi:[0,1]
	v_sub_f32_e32 v80, v230, v246
	v_exp_f32_e32 v234, v80
	v_sub_f32_e32 v80, v231, v246
	v_exp_f32_e32 v79, v79
	v_exp_f32_e32 v90, v80
	v_sub_f32_e32 v80, v232, v246
	v_exp_f32_e32 v80, v80
	v_add_f32_e32 v91, v79, v234
	v_sub_f32_e32 v74, v74, v246
	v_sub_f32_e32 v70, v70, v246
	v_pk_add_f32 v[92:93], v[90:91], v[80:81]
	v_sub_f32_e32 v81, v184, v246
	v_pk_add_f32 v[92:93], v[92:93], v[92:93] op_sel_hi:[0,1]
	v_sub_f32_e32 v91, v185, v246
	v_sub_f32_e32 v92, v227, v246
	v_exp_f32_e32 v81, v81
	v_exp_f32_e32 v91, v91
	v_exp_f32_e32 v94, v92
	v_sub_f32_e32 v92, v228, v246
	v_exp_f32_e32 v92, v92
	v_add_f32_e32 v95, v81, v91
	v_sub_f32_e32 v66, v66, v246
	v_pk_add_f32 v[96:97], v[94:95], v[92:93]
	v_exp_f32_e32 v93, v86
	v_sub_f32_e32 v86, v87, v246
	v_pk_add_f32 v[96:97], v[96:97], v[96:97] op_sel_hi:[0,1]
	v_exp_f32_e32 v95, v86
	v_sub_f32_e32 v86, v88, v246
	v_sub_f32_e32 v87, v89, v246
	v_exp_f32_e32 v86, v86
	v_exp_f32_e32 v96, v87
	v_add_f32_e32 v87, v93, v95
	v_pk_add_f32 v[88:89], v[86:87], v[96:97]
	v_exp_f32_e32 v87, v82
	v_sub_f32_e32 v82, v83, v246
	v_pk_add_f32 v[88:89], v[88:89], v[88:89] op_sel_hi:[0,1]
	v_exp_f32_e32 v97, v82
	v_sub_f32_e32 v82, v84, v246
	v_sub_f32_e32 v83, v85, v246
	v_exp_f32_e32 v82, v82
	v_exp_f32_e32 v88, v83
	v_add_f32_e32 v83, v87, v97
	v_pk_add_f32 v[84:85], v[82:83], v[88:89]
	v_exp_f32_e32 v83, v74
	v_sub_f32_e32 v74, v75, v246
	v_exp_f32_e32 v89, v74
	v_sub_f32_e32 v74, v76, v246
	v_pk_add_f32 v[84:85], v[84:85], v[84:85] op_sel_hi:[0,1]
	v_exp_f32_e32 v76, v74
	v_sub_f32_e32 v74, v77, v246
	v_exp_f32_e32 v84, v74
	v_add_f32_e32 v77, v83, v89
	v_pk_add_f32 v[74:75], v[76:77], v[84:85]
	v_exp_f32_e32 v77, v70
	v_sub_f32_e32 v70, v71, v246
	v_exp_f32_e32 v85, v70
	v_sub_f32_e32 v70, v72, v246
	v_pk_add_f32 v[184:185], v[74:75], v[74:75] op_sel_hi:[0,1]
	v_exp_f32_e32 v228, v70
	v_sub_f32_e32 v70, v73, v246
	v_exp_f32_e32 v184, v70
	v_add_f32_e32 v229, v77, v85
	v_cvt_pk_bf16_f32 v72, v91, v92
	v_cvt_pk_bf16_f32 v73, v95, v96
	v_pk_add_f32 v[70:71], v[228:229], v[184:185]
	v_exp_f32_e32 v185, v66
	v_sub_f32_e32 v66, v67, v246
	v_exp_f32_e32 v227, v66
	v_sub_f32_e32 v66, v68, v246
	v_pk_add_f32 v[230:231], v[70:71], v[70:71] op_sel_hi:[0,1]
	v_exp_f32_e32 v232, v66
	v_sub_f32_e32 v66, v69, v246
	v_exp_f32_e32 v230, v66
	v_add_f32_e32 v233, v185, v227
	v_cvt_pk_bf16_f32 v68, v81, v94
	v_cvt_pk_bf16_f32 v69, v93, v86
	v_pk_add_f32 v[66:67], v[232:233], v[230:231]
	v_cvt_pk_bf16_f32 v70, v237, v188
	v_add_f32_e32 v66, v66, v67
	v_add_f32_e32 v224, v224, v66
	v_cvt_pk_bf16_f32 v66, v236, v78
	v_cvt_pk_bf16_f32 v67, v79, v90
	v_cvt_pk_bf16_f32 v71, v234, v80
	v_cvt_pk_bf16_f32 v74, v87, v82
	v_cvt_pk_bf16_f32 v75, v83, v76
	v_cvt_pk_bf16_f32 v76, v77, v228
	v_cvt_pk_bf16_f32 v77, v185, v232
	v_cvt_pk_bf16_f32 v78, v97, v88
	v_cvt_pk_bf16_f32 v79, v89, v84
	v_cvt_pk_bf16_f32 v80, v85, v184
	v_cvt_pk_bf16_f32 v81, v227, v230
	ds_read_b128 v[82:85], v221 offset:17472
	ds_read_b128 v[86:89], v221 offset:17504
	ds_read_b128 v[90:93], v221 offset:22080
	ds_read_b128 v[94:97], v221 offset:22112
	ds_read_b128 v[228:231], v221 offset:26688
	ds_read_b128 v[232:235], v221 offset:26720
	ds_read_b128 v[236:239], v221 offset:31296
	ds_read_b128 v[240:243], v221 offset:31328
	v_mfma_f32_32x32x16_bf16 v[50:65], v[162:165], v[66:69], v[50:65]
	v_mfma_f32_32x32x16_bf16 v[34:49], v[166:169], v[66:69], v[34:49]
	v_mfma_f32_32x32x16_bf16 v[18:33], v[170:173], v[66:69], v[18:33]
	v_mfma_f32_32x32x16_bf16 v[2:17], v[174:177], v[66:69], v[2:17]
	v_mfma_f32_32x32x16_bf16 v[50:65], v[146:149], v[74:77], v[50:65]
	v_mfma_f32_32x32x16_bf16 v[34:49], v[150:153], v[74:77], v[34:49]
	v_mfma_f32_32x32x16_bf16 v[18:33], v[154:157], v[74:77], v[18:33]
	v_mfma_f32_32x32x16_bf16 v[2:17], v[158:161], v[74:77], v[2:17]
	s_waitcnt lgkmcnt(7)
	v_mfma_f32_32x32x16_bf16 v[50:65], v[82:85], v[70:73], v[50:65]
	s_waitcnt lgkmcnt(5)
	v_mfma_f32_32x32x16_bf16 v[34:49], v[90:93], v[70:73], v[34:49]
	s_waitcnt lgkmcnt(3)
	v_mfma_f32_32x32x16_bf16 v[18:33], v[228:231], v[70:73], v[18:33]
	s_waitcnt lgkmcnt(1)
	v_mfma_f32_32x32x16_bf16 v[2:17], v[236:239], v[70:73], v[2:17]
	v_mfma_f32_32x32x16_bf16 v[50:65], v[86:89], v[78:81], v[50:65]
	v_mfma_f32_32x32x16_bf16 v[34:49], v[94:97], v[78:81], v[34:49]
	v_mfma_f32_32x32x16_bf16 v[18:33], v[232:235], v[78:81], v[18:33]
	s_waitcnt lgkmcnt(0)
	v_mfma_f32_32x32x16_bf16 v[2:17], v[240:243], v[78:81], v[2:17]

.LBB0_1398:
	s_waitcnt lgkmcnt(7)
	v_mfma_f32_32x32x16_bf16 v[82:97], v[66:69], v[130:133], 0
	s_waitcnt lgkmcnt(5)
	v_mfma_f32_32x32x16_bf16 v[66:81], v[70:73], v[130:133], 0
	v_mfma_f32_32x32x16_bf16 v[82:97], v[146:149], v[134:137], v[82:97]
	s_waitcnt lgkmcnt(4)
	v_mfma_f32_32x32x16_bf16 v[66:81], v[150:153], v[134:137], v[66:81]
	s_waitcnt lgkmcnt(3)
	v_mfma_f32_32x32x16_bf16 v[82:97], v[154:157], v[138:141], v[82:97]
	s_waitcnt lgkmcnt(1)
	v_mfma_f32_32x32x16_bf16 v[66:81], v[162:165], v[138:141], v[66:81]
	v_mfma_f32_32x32x16_bf16 v[82:97], v[158:161], v[142:145], v[82:97]
	ds_read_b128 v[166:169], v221 offset:53248
	ds_read_b128 v[150:153], v221 offset:53280
	ds_read_b128 v[162:165], v225 offset:13824
	ds_read_b128 v[146:149], v225 offset:13856
	ds_read_b128 v[170:173], v221 offset:57856
	ds_read_b128 v[154:157], v221 offset:57888
	ds_read_b128 v[174:177], v221 offset:62464
	ds_read_b128 v[158:161], v221 offset:62496
	s_waitcnt lgkmcnt(8)
	v_mfma_f32_32x32x16_bf16 v[66:81], v[228:231], v[142:145], v[66:81]
	v_add_u32_e32 v184, s12, v223
	v_add_u32_e32 v184, 0x100, v184
	v_cvt_f32_i32_e32 v236, v184
	v_mul_f32_e64 v245, -v201, v236
	v_mov_b32_e32 v188, v82
	v_fmamk_f32 v234, v201, 0x3f800000, v83
	v_fmamk_f32 v229, v201, 0x40000000, v84
	v_fmamk_f32 v231, v201, 0x40400000, v85
	v_fmamk_f32 v184, v201, 0x41000000, v86
	v_fmamk_f32 v227, v201, 0x41100000, v87
	v_fmamk_f32 v86, v201, 0x41200000, v88
	v_fmamk_f32 v88, v201, 0x41300000, v89
	v_fmamk_f32 v233, v201, 0x42000000, v66
	v_fmamk_f32 v235, v201, 0x42040000, v67
	v_fmamk_f32 v230, v201, 0x42080000, v68
	v_fmamk_f32 v232, v201, 0x420c0000, v69
	v_fmamk_f32 v185, v201, 0x42200000, v70
	v_fmamk_f32 v228, v201, 0x42240000, v71
	v_fmamk_f32 v87, v201, 0x42280000, v72
	v_fmamk_f32 v89, v201, 0x422c0000, v73
	v_fmamk_f32 v82, v201, 0x41800000, v90
	v_fmamk_f32 v84, v201, 0x41880000, v91
	v_fmamk_f32 v83, v201, 0x42400000, v74
	v_fmamk_f32 v85, v201, 0x42440000, v75
	v_fmamk_f32 v74, v201, 0x41900000, v92
	v_fmamk_f32 v75, v201, 0x42480000, v76
	v_fmamk_f32 v76, v201, 0x41980000, v93
	v_fmamk_f32 v77, v201, 0x424c0000, v77
	v_fmamk_f32 v70, v201, 0x41c00000, v94
	v_fmamk_f32 v72, v201, 0x41c80000, v95
	v_fmamk_f32 v71, v201, 0x42600000, v78
	v_fmamk_f32 v73, v201, 0x42640000, v79
	v_fmamk_f32 v67, v201, 0x42680000, v80
	v_fmamk_f32 v69, v201, 0x426c0000, v81
	v_fmamk_f32 v66, v201, 0x41d00000, v96
	v_fmamk_f32 v68, v201, 0x41d80000, v97
.LBB0_1400:
	v_sub_f32_e32 v246, v226, v245
	v_sub_f32_e32 v78, v188, v246
	v_exp_f32_e32 v236, v78
	v_sub_f32_e32 v78, v233, v246
	v_exp_f32_e32 v237, v78
	v_sub_f32_e32 v78, v234, v246
	v_sub_f32_e32 v79, v235, v246
	v_exp_f32_e32 v78, v78
	v_exp_f32_e32 v188, v79
	v_add_f32_e32 v79, v236, v237
	v_sub_f32_e32 v86, v86, v246
	v_sub_f32_e32 v82, v82, v246
	v_pk_add_f32 v[80:81], v[78:79], v[188:189]
	v_sub_f32_e32 v79, v229, v246
	v_pk_add_f32 v[80:81], v[80:81], v[80:81] op_sel_hi:[0,1]
	v_sub_f32_e32 v80, v230, v246
	v_exp_f32_e32 v234, v80
	v_sub_f32_e32 v80, v231, v246
	v_exp_f32_e32 v79, v79
	v_exp_f32_e32 v90, v80
	v_sub_f32_e32 v80, v232, v246
	v_exp_f32_e32 v80, v80
	v_add_f32_e32 v91, v79, v234
	v_sub_f32_e32 v74, v74, v246
	v_sub_f32_e32 v70, v70, v246
	v_pk_add_f32 v[92:93], v[90:91], v[80:81]
	v_sub_f32_e32 v81, v184, v246
	v_pk_add_f32 v[92:93], v[92:93], v[92:93] op_sel_hi:[0,1]
	v_sub_f32_e32 v91, v185, v246
	v_sub_f32_e32 v92, v227, v246
	v_exp_f32_e32 v81, v81
	v_exp_f32_e32 v91, v91
	v_exp_f32_e32 v94, v92
	v_sub_f32_e32 v92, v228, v246
	v_exp_f32_e32 v92, v92
	v_add_f32_e32 v95, v81, v91
	v_sub_f32_e32 v66, v66, v246
	v_pk_add_f32 v[96:97], v[94:95], v[92:93]
	v_exp_f32_e32 v93, v86
	v_sub_f32_e32 v86, v87, v246
	v_pk_add_f32 v[96:97], v[96:97], v[96:97] op_sel_hi:[0,1]
	v_exp_f32_e32 v95, v86
	v_sub_f32_e32 v86, v88, v246
	v_sub_f32_e32 v87, v89, v246
	v_exp_f32_e32 v86, v86
	v_exp_f32_e32 v96, v87
	v_add_f32_e32 v87, v93, v95
	v_pk_add_f32 v[88:89], v[86:87], v[96:97]
	v_exp_f32_e32 v87, v82
	v_sub_f32_e32 v82, v83, v246
	v_pk_add_f32 v[88:89], v[88:89], v[88:89] op_sel_hi:[0,1]
	v_exp_f32_e32 v97, v82
	v_sub_f32_e32 v82, v84, v246
	v_sub_f32_e32 v83, v85, v246
	v_exp_f32_e32 v82, v82
	v_exp_f32_e32 v88, v83
	v_add_f32_e32 v83, v87, v97
	v_pk_add_f32 v[84:85], v[82:83], v[88:89]
	v_exp_f32_e32 v83, v74
	v_sub_f32_e32 v74, v75, v246
	v_exp_f32_e32 v89, v74
	v_sub_f32_e32 v74, v76, v246
	v_pk_add_f32 v[84:85], v[84:85], v[84:85] op_sel_hi:[0,1]
	v_exp_f32_e32 v76, v74
	v_sub_f32_e32 v74, v77, v246
	v_exp_f32_e32 v84, v74
	v_add_f32_e32 v77, v83, v89
	v_pk_add_f32 v[74:75], v[76:77], v[84:85]
	v_exp_f32_e32 v77, v70
	v_sub_f32_e32 v70, v71, v246
	v_exp_f32_e32 v85, v70
	v_sub_f32_e32 v70, v72, v246
	v_pk_add_f32 v[184:185], v[74:75], v[74:75] op_sel_hi:[0,1]
	v_exp_f32_e32 v228, v70
	v_sub_f32_e32 v70, v73, v246
	v_exp_f32_e32 v184, v70
	v_add_f32_e32 v229, v77, v85
	v_cvt_pk_bf16_f32 v72, v91, v92
	v_cvt_pk_bf16_f32 v73, v95, v96
	v_pk_add_f32 v[70:71], v[228:229], v[184:185]
	v_exp_f32_e32 v185, v66
	v_sub_f32_e32 v66, v67, v246
	v_exp_f32_e32 v227, v66
	v_sub_f32_e32 v66, v68, v246
	v_pk_add_f32 v[230:231], v[70:71], v[70:71] op_sel_hi:[0,1]
	v_exp_f32_e32 v232, v66
	v_sub_f32_e32 v66, v69, v246
	v_exp_f32_e32 v230, v66
	v_add_f32_e32 v233, v185, v227
	v_cvt_pk_bf16_f32 v68, v81, v94
	v_cvt_pk_bf16_f32 v69, v93, v86
	v_pk_add_f32 v[66:67], v[232:233], v[230:231]
	v_cvt_pk_bf16_f32 v70, v237, v188
	v_add_f32_e32 v66, v66, v67
	v_add_f32_e32 v224, v224, v66
	v_cvt_pk_bf16_f32 v66, v236, v78
	v_cvt_pk_bf16_f32 v67, v79, v90
	v_cvt_pk_bf16_f32 v71, v234, v80
	v_cvt_pk_bf16_f32 v74, v87, v82
	v_cvt_pk_bf16_f32 v75, v83, v76
	v_cvt_pk_bf16_f32 v76, v77, v228
	v_cvt_pk_bf16_f32 v77, v185, v232
	v_cvt_pk_bf16_f32 v78, v97, v88
	v_cvt_pk_bf16_f32 v79, v89, v84
	v_cvt_pk_bf16_f32 v80, v85, v184
	v_cvt_pk_bf16_f32 v81, v227, v230
	ds_read_b128 v[82:85], v221 offset:53312
	ds_read_b128 v[86:89], v221 offset:53344
	ds_read_b128 v[90:93], v221 offset:57920
	ds_read_b128 v[94:97], v221 offset:57952
	ds_read_b128 v[228:231], v221 offset:62528
	ds_read_b128 v[232:235], v221 offset:62560
	ds_read_b128 v[236:239], v225 offset:13888
	ds_read_b128 v[240:243], v225 offset:13920
	v_mfma_f32_32x32x16_bf16 v[50:65], v[166:169], v[66:69], v[50:65]
	v_mfma_f32_32x32x16_bf16 v[34:49], v[170:173], v[66:69], v[34:49]
	v_mfma_f32_32x32x16_bf16 v[18:33], v[174:177], v[66:69], v[18:33]
	v_mfma_f32_32x32x16_bf16 v[2:17], v[162:165], v[66:69], v[2:17]
	v_mfma_f32_32x32x16_bf16 v[50:65], v[150:153], v[74:77], v[50:65]
	v_mfma_f32_32x32x16_bf16 v[34:49], v[154:157], v[74:77], v[34:49]
	v_mfma_f32_32x32x16_bf16 v[18:33], v[158:161], v[74:77], v[18:33]
	v_mfma_f32_32x32x16_bf16 v[2:17], v[146:149], v[74:77], v[2:17]
	s_waitcnt lgkmcnt(7)
	v_mfma_f32_32x32x16_bf16 v[50:65], v[82:85], v[70:73], v[50:65]
	s_waitcnt lgkmcnt(5)
	v_mfma_f32_32x32x16_bf16 v[34:49], v[90:93], v[70:73], v[34:49]
	s_waitcnt lgkmcnt(3)
	v_mfma_f32_32x32x16_bf16 v[18:33], v[228:231], v[70:73], v[18:33]
	s_waitcnt lgkmcnt(1)
	v_mfma_f32_32x32x16_bf16 v[2:17], v[236:239], v[70:73], v[2:17]
	v_mfma_f32_32x32x16_bf16 v[50:65], v[86:89], v[78:81], v[50:65]
	v_mfma_f32_32x32x16_bf16 v[34:49], v[94:97], v[78:81], v[34:49]
	v_mfma_f32_32x32x16_bf16 v[18:33], v[232:235], v[78:81], v[18:33]
	s_waitcnt lgkmcnt(0)
	v_mfma_f32_32x32x16_bf16 v[2:17], v[240:243], v[78:81], v[2:17]
	s_cmp_ge_i32 s46, s26
	s_cbranch_scc1 .LBB0_1379

	.amdhsa_kernel _Z14fwd_megakernel6Params
		.amdhsa_group_segment_fixed_size 0
		.amdhsa_private_segment_fixed_size 0
		.amdhsa_kernarg_size 536
		.amdhsa_user_sgpr_count 2
		.amdhsa_user_sgpr_dispatch_ptr 0
		.amdhsa_user_sgpr_queue_ptr 0
		.amdhsa_user_sgpr_kernarg_segment_ptr 1
		.amdhsa_user_sgpr_dispatch_id 0
		.amdhsa_user_sgpr_kernarg_preload_length 0
		.amdhsa_user_sgpr_kernarg_preload_offset 0
		.amdhsa_user_sgpr_private_segment_size 0
		.amdhsa_uses_dynamic_stack 0
		.amdhsa_enable_private_segment 0
		.amdhsa_system_sgpr_workgroup_id_x 1
		.amdhsa_system_sgpr_workgroup_id_y 0
		.amdhsa_system_sgpr_workgroup_id_z 0
		.amdhsa_system_sgpr_workgroup_info 0
		.amdhsa_system_vgpr_workitem_id 0
		.amdhsa_next_free_vgpr 254
		.amdhsa_next_free_sgpr 100
		.amdhsa_accum_offset 256
		.amdhsa_reserve_vcc 1
		.amdhsa_float_round_mode_32 0
		.amdhsa_float_round_mode_16_64 0
		.amdhsa_float_denorm_mode_32 3
		.amdhsa_float_denorm_mode_16_64 3
		.amdhsa_dx10_clamp 1
		.amdhsa_ieee_mode 1
		.amdhsa_fp16_overflow 0
		.amdhsa_tg_split 0
		.amdhsa_exception_fp_ieee_invalid_op 0
		.amdhsa_exception_fp_denorm_src 0
		.amdhsa_exception_fp_ieee_div_zero 0
		.amdhsa_exception_fp_ieee_overflow 0
		.amdhsa_exception_fp_ieee_underflow 0
		.amdhsa_exception_fp_ieee_inexact 0
		.amdhsa_exception_int_div_zero 0
	.end_amdhsa_kernel

amdhsa.kernels:
  - .agpr_count:     0
    .args:
      - .offset:         0
        .size:           280
        .value_kind:     by_value
      - .offset:         280
        .size:           4
        .value_kind:     hidden_block_count_x
      - .offset:         284
        .size:           4
        .value_kind:     hidden_block_count_y
      - .offset:         288
        .size:           4
        .value_kind:     hidden_block_count_z
      - .offset:         292
        .size:           2
        .value_kind:     hidden_group_size_x
      - .offset:         294
        .size:           2
        .value_kind:     hidden_group_size_y
      - .offset:         296
        .size:           2
        .value_kind:     hidden_group_size_z
      - .offset:         298
        .size:           2
        .value_kind:     hidden_remainder_x
      - .offset:         300
        .size:           2
        .value_kind:     hidden_remainder_y
      - .offset:         302
        .size:           2
        .value_kind:     hidden_remainder_z
      - .offset:         320
        .size:           8
        .value_kind:     hidden_global_offset_x
      - .offset:         328
        .size:           8
        .value_kind:     hidden_global_offset_y
      - .offset:         336
        .size:           8
        .value_kind:     hidden_global_offset_z
      - .offset:         344
        .size:           2
        .value_kind:     hidden_grid_dims
      - .offset:         400
        .size:           4
        .value_kind:     hidden_dynamic_lds_size
    .group_segment_fixed_size: 0
    .kernarg_segment_align: 8
    .kernarg_segment_size: 536
    .language:       OpenCL C
    .language_version:
      - 2
      - 0
    .max_flat_workgroup_size: 512
    .name:           _Z14fwd_megakernel6Params
    .private_segment_fixed_size: 0
    .sgpr_count:     106
    .sgpr_spill_count: 56
    .symbol:         _Z14fwd_megakernel6Params.kd
    .uniform_work_group_size: 1
    .uses_dynamic_stack: false
    .vgpr_count:     254
    .vgpr_spill_count: 0
    .wavefront_size: 64
